# attention masked key tiles: tile-uniform sequence bounds folded into one scalar limit, band test as add/compare/select per element (3 VALU instead of 5 VALU + 2 SALU)
# speedup vs baseline: 1.0054x; 1.0054x over previous
.LBB0_630:
	s_andn2_b64 vcc, exec, s[0:1]
	s_cbranch_vccnz .LBB0_632
	s_nop 7
	v_add_u32_e32 v204, s74, v188
	s_add_i32 s4, s72, 0xffffff80
	s_cmp_gt_i32 s4, -1
	s_cselect_b32 s5, s75, 0
	s_cmp_lt_i32 s4, s71
	s_cselect_b32 s4, s5, 0
	v_add_u32_e32 v212, 0x100, v204
	v_add_u32_e32 v203, 0xff, v204
	v_cmp_gt_u32_e32 vcc, s4, v212
	v_cmp_gt_u32_e64 s[6:7], s4, v203
	v_add_u32_e32 v212, 0xfe, v204
	v_cndmask_b32_e32 v114, v221, v114, vcc
	v_add_u32_e32 v203, 0xfd, v204
	v_cndmask_b32_e64 v115, v221, v115, s[6:7]
	v_cmp_gt_u32_e32 vcc, s4, v212
	v_cmp_gt_u32_e64 s[6:7], s4, v203
	v_add_u32_e32 v212, 0xf8, v204
	v_cndmask_b32_e32 v116, v221, v116, vcc
	v_add_u32_e32 v203, 0xf7, v204
	v_cndmask_b32_e64 v117, v221, v117, s[6:7]
	v_cmp_gt_u32_e32 vcc, s4, v212
	v_cmp_gt_u32_e64 s[6:7], s4, v203
	v_add_u32_e32 v212, 0xf6, v204
	v_cndmask_b32_e32 v118, v221, v118, vcc
	v_add_u32_e32 v203, 0xf5, v204
	v_cndmask_b32_e64 v119, v221, v119, s[6:7]
	v_cmp_gt_u32_e32 vcc, s4, v212
	v_cmp_gt_u32_e64 s[6:7], s4, v203
	v_add_u32_e32 v212, 0xf0, v204
	v_cndmask_b32_e32 v120, v221, v120, vcc
	v_add_u32_e32 v203, 0xef, v204
	v_cndmask_b32_e64 v121, v221, v121, s[6:7]
	v_cmp_gt_u32_e32 vcc, s4, v212
	v_cmp_gt_u32_e64 s[6:7], s4, v203
	v_add_u32_e32 v212, 0xee, v204
	v_cndmask_b32_e32 v122, v221, v122, vcc
	v_add_u32_e32 v203, 0xed, v204
	v_cndmask_b32_e64 v123, v221, v123, s[6:7]
	v_cmp_gt_u32_e32 vcc, s4, v212
	v_cmp_gt_u32_e64 s[6:7], s4, v203
	v_add_u32_e32 v212, 0xe8, v204
	v_cndmask_b32_e32 v124, v221, v124, vcc
	v_add_u32_e32 v203, 0xe7, v204
	v_cndmask_b32_e64 v125, v221, v125, s[6:7]
	v_cmp_gt_u32_e32 vcc, s4, v212
	v_cmp_gt_u32_e64 s[6:7], s4, v203
	v_add_u32_e32 v212, 0xe6, v204
	v_cndmask_b32_e32 v126, v221, v126, vcc
	v_add_u32_e32 v203, 0xe5, v204
	v_cndmask_b32_e64 v127, v221, v127, s[6:7]
	v_cmp_gt_u32_e32 vcc, s4, v212
	v_cmp_gt_u32_e64 s[6:7], s4, v203
	v_add_u32_e32 v212, 0xe0, v204
	v_cndmask_b32_e32 v128, v221, v128, vcc
	v_add_u32_e32 v203, 0xdf, v204
	v_cndmask_b32_e64 v129, v221, v129, s[6:7]
	v_cmp_gt_u32_e32 vcc, s4, v212
	v_cmp_gt_u32_e64 s[6:7], s4, v203
	v_add_u32_e32 v212, 0xde, v204
	v_cndmask_b32_e32 v98, v221, v98, vcc
	v_add_u32_e32 v203, 0xdd, v204
	v_cndmask_b32_e64 v99, v221, v99, s[6:7]
	v_cmp_gt_u32_e32 vcc, s4, v212
	v_cmp_gt_u32_e64 s[6:7], s4, v203
	v_add_u32_e32 v212, 0xd8, v204
	v_cndmask_b32_e32 v100, v221, v100, vcc
	v_add_u32_e32 v203, 0xd7, v204
	v_cndmask_b32_e64 v101, v221, v101, s[6:7]
	v_cmp_gt_u32_e32 vcc, s4, v212
	v_cmp_gt_u32_e64 s[6:7], s4, v203
	v_add_u32_e32 v212, 0xd6, v204
	v_cndmask_b32_e32 v102, v221, v102, vcc
	v_add_u32_e32 v203, 0xd5, v204
	v_cndmask_b32_e64 v103, v221, v103, s[6:7]
	v_cmp_gt_u32_e32 vcc, s4, v212
	v_cmp_gt_u32_e64 s[6:7], s4, v203
	v_add_u32_e32 v212, 0xd0, v204
	v_cndmask_b32_e32 v104, v221, v104, vcc
	v_add_u32_e32 v203, 0xcf, v204
	v_cndmask_b32_e64 v105, v221, v105, s[6:7]
	v_cmp_gt_u32_e32 vcc, s4, v212
	v_cmp_gt_u32_e64 s[6:7], s4, v203
	v_add_u32_e32 v212, 0xce, v204
	v_cndmask_b32_e32 v106, v221, v106, vcc
	v_add_u32_e32 v203, 0xcd, v204
	v_cndmask_b32_e64 v107, v221, v107, s[6:7]
	v_cmp_gt_u32_e32 vcc, s4, v212
	v_cmp_gt_u32_e64 s[6:7], s4, v203
	v_add_u32_e32 v212, 0xc8, v204
	v_cndmask_b32_e32 v108, v221, v108, vcc
	v_add_u32_e32 v203, 0xc7, v204
	v_cndmask_b32_e64 v109, v221, v109, s[6:7]
	v_cmp_gt_u32_e32 vcc, s4, v212
	v_cmp_gt_u32_e64 s[6:7], s4, v203
	v_add_u32_e32 v212, 0xc6, v204
	v_cndmask_b32_e32 v110, v221, v110, vcc
	v_add_u32_e32 v203, 0xc5, v204
	v_cndmask_b32_e64 v111, v221, v111, s[6:7]
	v_cmp_gt_u32_e32 vcc, s4, v212
	v_cmp_gt_u32_e64 s[6:7], s4, v203
	s_nop 1
	v_cndmask_b32_e32 v112, v221, v112, vcc
	v_cndmask_b32_e64 v113, v221, v113, s[6:7]
	v_max3_f32 v201, v114, v221, v115
	v_max3_f32 v201, v201, v116, v117
	v_max3_f32 v201, v201, v118, v119
	v_max3_f32 v201, v201, v120, v121
	v_max3_f32 v201, v201, v122, v123
	v_max3_f32 v201, v201, v124, v125
	v_max3_f32 v201, v201, v126, v127
	v_max3_f32 v201, v201, v128, v129
	v_max3_f32 v201, v201, v98, v99
	v_max3_f32 v201, v201, v100, v101
	v_max3_f32 v201, v201, v102, v103
	v_max3_f32 v201, v201, v104, v105
	v_max3_f32 v201, v201, v106, v107
	v_max3_f32 v201, v201, v108, v109
	v_max3_f32 v201, v201, v110, v111
	v_max3_f32 v201, v201, v112, v113

.LBB0_636:
	s_andn2_b64 vcc, exec, s[0:1]
	s_movk_i32 s94, 0x1000
	s_mov_b32 s8, 0x15800
	s_cbranch_vccnz .LBB0_638
	s_add_i32 s4, s72, 0xffffff80
	s_cmp_gt_i32 s4, -1
	s_cselect_b32 s5, s75, 0
	s_cmp_lt_i32 s4, s71
	s_cselect_b32 s4, s5, 0
	v_add_u32_e32 v102, 0x120, v204
	v_add_u32_e32 v203, 0x11f, v204
	v_cmp_gt_u32_e32 vcc, s4, v102
	v_cmp_gt_u32_e64 s[6:7], s4, v203
	v_add_u32_e32 v102, 0x11e, v204
	v_cndmask_b32_e32 v82, v221, v82, vcc
	v_add_u32_e32 v203, 0x11d, v204
	v_cndmask_b32_e64 v83, v221, v83, s[6:7]
	v_cmp_gt_u32_e32 vcc, s4, v102
	v_cmp_gt_u32_e64 s[6:7], s4, v203
	v_add_u32_e32 v102, 0x118, v204
	v_cndmask_b32_e32 v84, v221, v84, vcc
	v_add_u32_e32 v203, 0x117, v204
	v_cndmask_b32_e64 v85, v221, v85, s[6:7]
	v_cmp_gt_u32_e32 vcc, s4, v102
	v_cmp_gt_u32_e64 s[6:7], s4, v203
	v_add_u32_e32 v102, 0x116, v204
	v_cndmask_b32_e32 v86, v221, v86, vcc
	v_add_u32_e32 v203, 0x115, v204
	v_cndmask_b32_e64 v87, v221, v87, s[6:7]
	v_cmp_gt_u32_e32 vcc, s4, v102
	v_cmp_gt_u32_e64 s[6:7], s4, v203
	v_add_u32_e32 v102, 0x110, v204
	v_cndmask_b32_e32 v88, v221, v88, vcc
	v_add_u32_e32 v203, 0x10f, v204
	v_cndmask_b32_e64 v89, v221, v89, s[6:7]
	v_cmp_gt_u32_e32 vcc, s4, v102
	v_cmp_gt_u32_e64 s[6:7], s4, v203
	v_add_u32_e32 v102, 0x10e, v204
	v_cndmask_b32_e32 v90, v221, v90, vcc
	v_add_u32_e32 v203, 0x10d, v204
	v_cndmask_b32_e64 v91, v221, v91, s[6:7]
	v_cmp_gt_u32_e32 vcc, s4, v102
	v_cmp_gt_u32_e64 s[6:7], s4, v203
	v_add_u32_e32 v102, 0x108, v204
	v_cndmask_b32_e32 v92, v221, v92, vcc
	v_add_u32_e32 v203, 0x107, v204
	v_cndmask_b32_e64 v93, v221, v93, s[6:7]
	v_cmp_gt_u32_e32 vcc, s4, v102
	v_cmp_gt_u32_e64 s[6:7], s4, v203
	v_add_u32_e32 v102, 0x106, v204
	v_cndmask_b32_e32 v94, v221, v94, vcc
	v_add_u32_e32 v203, 0x105, v204
	v_cndmask_b32_e64 v95, v221, v95, s[6:7]
	v_cmp_gt_u32_e32 vcc, s4, v102
	v_cmp_gt_u32_e64 s[6:7], s4, v203
	v_add_u32_e32 v102, 0x100, v204
	v_cndmask_b32_e32 v96, v221, v96, vcc
	v_add_u32_e32 v203, 0xff, v204
	v_cndmask_b32_e64 v97, v221, v97, s[6:7]
	v_cmp_gt_u32_e32 vcc, s4, v102
	v_cmp_gt_u32_e64 s[6:7], s4, v203
	v_add_u32_e32 v102, 0xfe, v204
	v_cndmask_b32_e32 v66, v221, v66, vcc
	v_add_u32_e32 v203, 0xfd, v204
	v_cndmask_b32_e64 v67, v221, v67, s[6:7]
	v_cmp_gt_u32_e32 vcc, s4, v102
	v_cmp_gt_u32_e64 s[6:7], s4, v203
	v_add_u32_e32 v102, 0xf8, v204
	v_cndmask_b32_e32 v68, v221, v68, vcc
	v_add_u32_e32 v203, 0xf7, v204
	v_cndmask_b32_e64 v69, v221, v69, s[6:7]
	v_cmp_gt_u32_e32 vcc, s4, v102
	v_cmp_gt_u32_e64 s[6:7], s4, v203
	v_add_u32_e32 v102, 0xf6, v204
	v_cndmask_b32_e32 v70, v221, v70, vcc
	v_add_u32_e32 v203, 0xf5, v204
	v_cndmask_b32_e64 v71, v221, v71, s[6:7]
	v_cmp_gt_u32_e32 vcc, s4, v102
	v_cmp_gt_u32_e64 s[6:7], s4, v203
	v_add_u32_e32 v102, 0xf0, v204
	v_cndmask_b32_e32 v72, v221, v72, vcc
	v_add_u32_e32 v203, 0xef, v204
	v_cndmask_b32_e64 v73, v221, v73, s[6:7]
	v_cmp_gt_u32_e32 vcc, s4, v102
	v_cmp_gt_u32_e64 s[6:7], s4, v203
	v_add_u32_e32 v102, 0xee, v204
	v_cndmask_b32_e32 v74, v221, v74, vcc
	v_add_u32_e32 v203, 0xed, v204
	v_cndmask_b32_e64 v75, v221, v75, s[6:7]
	v_cmp_gt_u32_e32 vcc, s4, v102
	v_cmp_gt_u32_e64 s[6:7], s4, v203
	v_add_u32_e32 v102, 0xe8, v204
	v_cndmask_b32_e32 v76, v221, v76, vcc
	v_add_u32_e32 v203, 0xe7, v204
	v_cndmask_b32_e64 v77, v221, v77, s[6:7]
	v_cmp_gt_u32_e32 vcc, s4, v102
	v_cmp_gt_u32_e64 s[6:7], s4, v203
	v_add_u32_e32 v102, 0xe6, v204
	v_cndmask_b32_e32 v78, v221, v78, vcc
	v_add_u32_e32 v203, 0xe5, v204
	v_cndmask_b32_e64 v79, v221, v79, s[6:7]
	v_cmp_gt_u32_e32 vcc, s4, v102
	v_cmp_gt_u32_e64 s[6:7], s4, v203
	s_nop 1
	v_cndmask_b32_e32 v80, v221, v80, vcc
	v_cndmask_b32_e64 v81, v221, v81, s[6:7]
	v_max3_f32 v101, v82, v221, v83
	v_max3_f32 v101, v101, v84, v85
	v_max3_f32 v101, v101, v86, v87
	v_max3_f32 v101, v101, v88, v89
	v_max3_f32 v101, v101, v90, v91
	v_max3_f32 v101, v101, v92, v93
	v_max3_f32 v101, v101, v94, v95
	v_max3_f32 v101, v101, v96, v97
	v_max3_f32 v101, v101, v66, v67
	v_max3_f32 v101, v101, v68, v69
	v_max3_f32 v101, v101, v70, v71
	v_max3_f32 v101, v101, v72, v73
	v_max3_f32 v101, v101, v74, v75
	v_max3_f32 v101, v101, v76, v77
	v_max3_f32 v101, v101, v78, v79
	v_max3_f32 v101, v101, v80, v81

.LBB0_2212:
	s_andn2_b64 vcc, exec, s[0:1]
	s_cbranch_vccnz .LBB0_2214
	s_nop 7
	v_add_u32_e32 v204, s79, v188
	s_add_i32 s4, s72, 0xffffff80
	s_cmp_gt_i32 s4, -1
	s_cselect_b32 s5, s75, 0
	s_cmp_lt_i32 s4, s71
	s_cselect_b32 s4, s5, 0
	v_add_u32_e32 v212, 0x100, v204
	v_add_u32_e32 v203, 0xff, v204
	v_cmp_gt_u32_e32 vcc, s4, v212
	v_cmp_gt_u32_e64 s[6:7], s4, v203
	v_add_u32_e32 v212, 0xfe, v204
	v_cndmask_b32_e32 v114, v221, v114, vcc
	v_add_u32_e32 v203, 0xfd, v204
	v_cndmask_b32_e64 v115, v221, v115, s[6:7]
	v_cmp_gt_u32_e32 vcc, s4, v212
	v_cmp_gt_u32_e64 s[6:7], s4, v203
	v_add_u32_e32 v212, 0xf8, v204
	v_cndmask_b32_e32 v116, v221, v116, vcc
	v_add_u32_e32 v203, 0xf7, v204
	v_cndmask_b32_e64 v117, v221, v117, s[6:7]
	v_cmp_gt_u32_e32 vcc, s4, v212
	v_cmp_gt_u32_e64 s[6:7], s4, v203
	v_add_u32_e32 v212, 0xf6, v204
	v_cndmask_b32_e32 v118, v221, v118, vcc
	v_add_u32_e32 v203, 0xf5, v204
	v_cndmask_b32_e64 v119, v221, v119, s[6:7]
	v_cmp_gt_u32_e32 vcc, s4, v212
	v_cmp_gt_u32_e64 s[6:7], s4, v203
	v_add_u32_e32 v212, 0xf0, v204
	v_cndmask_b32_e32 v120, v221, v120, vcc
	v_add_u32_e32 v203, 0xef, v204
	v_cndmask_b32_e64 v121, v221, v121, s[6:7]
	v_cmp_gt_u32_e32 vcc, s4, v212
	v_cmp_gt_u32_e64 s[6:7], s4, v203
	v_add_u32_e32 v212, 0xee, v204
	v_cndmask_b32_e32 v122, v221, v122, vcc
	v_add_u32_e32 v203, 0xed, v204
	v_cndmask_b32_e64 v123, v221, v123, s[6:7]
	v_cmp_gt_u32_e32 vcc, s4, v212
	v_cmp_gt_u32_e64 s[6:7], s4, v203
	v_add_u32_e32 v212, 0xe8, v204
	v_cndmask_b32_e32 v124, v221, v124, vcc
	v_add_u32_e32 v203, 0xe7, v204
	v_cndmask_b32_e64 v125, v221, v125, s[6:7]
	v_cmp_gt_u32_e32 vcc, s4, v212
	v_cmp_gt_u32_e64 s[6:7], s4, v203
	v_add_u32_e32 v212, 0xe6, v204
	v_cndmask_b32_e32 v126, v221, v126, vcc
	v_add_u32_e32 v203, 0xe5, v204
	v_cndmask_b32_e64 v127, v221, v127, s[6:7]
	v_cmp_gt_u32_e32 vcc, s4, v212
	v_cmp_gt_u32_e64 s[6:7], s4, v203
	v_add_u32_e32 v212, 0xe0, v204
	v_cndmask_b32_e32 v128, v221, v128, vcc
	v_add_u32_e32 v203, 0xdf, v204
	v_cndmask_b32_e64 v129, v221, v129, s[6:7]
	v_cmp_gt_u32_e32 vcc, s4, v212
	v_cmp_gt_u32_e64 s[6:7], s4, v203
	v_add_u32_e32 v212, 0xde, v204
	v_cndmask_b32_e32 v98, v221, v98, vcc
	v_add_u32_e32 v203, 0xdd, v204
	v_cndmask_b32_e64 v99, v221, v99, s[6:7]
	v_cmp_gt_u32_e32 vcc, s4, v212
	v_cmp_gt_u32_e64 s[6:7], s4, v203
	v_add_u32_e32 v212, 0xd8, v204
	v_cndmask_b32_e32 v100, v221, v100, vcc
	v_add_u32_e32 v203, 0xd7, v204
	v_cndmask_b32_e64 v101, v221, v101, s[6:7]
	v_cmp_gt_u32_e32 vcc, s4, v212
	v_cmp_gt_u32_e64 s[6:7], s4, v203
	v_add_u32_e32 v212, 0xd6, v204
	v_cndmask_b32_e32 v102, v221, v102, vcc
	v_add_u32_e32 v203, 0xd5, v204
	v_cndmask_b32_e64 v103, v221, v103, s[6:7]
	v_cmp_gt_u32_e32 vcc, s4, v212
	v_cmp_gt_u32_e64 s[6:7], s4, v203
	v_add_u32_e32 v212, 0xd0, v204
	v_cndmask_b32_e32 v104, v221, v104, vcc
	v_add_u32_e32 v203, 0xcf, v204
	v_cndmask_b32_e64 v105, v221, v105, s[6:7]
	v_cmp_gt_u32_e32 vcc, s4, v212
	v_cmp_gt_u32_e64 s[6:7], s4, v203
	v_add_u32_e32 v212, 0xce, v204
	v_cndmask_b32_e32 v106, v221, v106, vcc
	v_add_u32_e32 v203, 0xcd, v204
	v_cndmask_b32_e64 v107, v221, v107, s[6:7]
	v_cmp_gt_u32_e32 vcc, s4, v212
	v_cmp_gt_u32_e64 s[6:7], s4, v203
	v_add_u32_e32 v212, 0xc8, v204
	v_cndmask_b32_e32 v108, v221, v108, vcc
	v_add_u32_e32 v203, 0xc7, v204
	v_cndmask_b32_e64 v109, v221, v109, s[6:7]
	v_cmp_gt_u32_e32 vcc, s4, v212
	v_cmp_gt_u32_e64 s[6:7], s4, v203
	v_add_u32_e32 v212, 0xc6, v204
	v_cndmask_b32_e32 v110, v221, v110, vcc
	v_add_u32_e32 v203, 0xc5, v204
	v_cndmask_b32_e64 v111, v221, v111, s[6:7]
	v_cmp_gt_u32_e32 vcc, s4, v212
	v_cmp_gt_u32_e64 s[6:7], s4, v203
	s_nop 1
	v_cndmask_b32_e32 v112, v221, v112, vcc
	v_cndmask_b32_e64 v113, v221, v113, s[6:7]
	v_max3_f32 v201, v114, v221, v115
	v_max3_f32 v201, v201, v116, v117
	v_max3_f32 v201, v201, v118, v119
	v_max3_f32 v201, v201, v120, v121
	v_max3_f32 v201, v201, v122, v123
	v_max3_f32 v201, v201, v124, v125
	v_max3_f32 v201, v201, v126, v127
	v_max3_f32 v201, v201, v128, v129
	v_max3_f32 v201, v201, v98, v99
	v_max3_f32 v201, v201, v100, v101
	v_max3_f32 v201, v201, v102, v103
	v_max3_f32 v201, v201, v104, v105
	v_max3_f32 v201, v201, v106, v107
	v_max3_f32 v201, v201, v108, v109
	v_max3_f32 v201, v201, v110, v111
	v_max3_f32 v201, v201, v112, v113

.LBB0_2218:
	s_andn2_b64 vcc, exec, s[0:1]
	s_cbranch_vccnz .LBB0_2220
	s_add_i32 s4, s72, 0xffffff80
	s_cmp_gt_i32 s4, -1
	s_cselect_b32 s5, s75, 0
	s_cmp_lt_i32 s4, s71
	s_cselect_b32 s4, s5, 0
	v_add_u32_e32 v102, 0x120, v204
	v_add_u32_e32 v203, 0x11f, v204
	v_cmp_gt_u32_e32 vcc, s4, v102
	v_cmp_gt_u32_e64 s[6:7], s4, v203
	v_add_u32_e32 v102, 0x11e, v204
	v_cndmask_b32_e32 v82, v221, v82, vcc
	v_add_u32_e32 v203, 0x11d, v204
	v_cndmask_b32_e64 v83, v221, v83, s[6:7]
	v_cmp_gt_u32_e32 vcc, s4, v102
	v_cmp_gt_u32_e64 s[6:7], s4, v203
	v_add_u32_e32 v102, 0x118, v204
	v_cndmask_b32_e32 v84, v221, v84, vcc
	v_add_u32_e32 v203, 0x117, v204
	v_cndmask_b32_e64 v85, v221, v85, s[6:7]
	v_cmp_gt_u32_e32 vcc, s4, v102
	v_cmp_gt_u32_e64 s[6:7], s4, v203
	v_add_u32_e32 v102, 0x116, v204
	v_cndmask_b32_e32 v86, v221, v86, vcc
	v_add_u32_e32 v203, 0x115, v204
	v_cndmask_b32_e64 v87, v221, v87, s[6:7]
	v_cmp_gt_u32_e32 vcc, s4, v102
	v_cmp_gt_u32_e64 s[6:7], s4, v203
	v_add_u32_e32 v102, 0x110, v204
	v_cndmask_b32_e32 v88, v221, v88, vcc
	v_add_u32_e32 v203, 0x10f, v204
	v_cndmask_b32_e64 v89, v221, v89, s[6:7]
	v_cmp_gt_u32_e32 vcc, s4, v102
	v_cmp_gt_u32_e64 s[6:7], s4, v203
	v_add_u32_e32 v102, 0x10e, v204
	v_cndmask_b32_e32 v90, v221, v90, vcc
	v_add_u32_e32 v203, 0x10d, v204
	v_cndmask_b32_e64 v91, v221, v91, s[6:7]
	v_cmp_gt_u32_e32 vcc, s4, v102
	v_cmp_gt_u32_e64 s[6:7], s4, v203
	v_add_u32_e32 v102, 0x108, v204
	v_cndmask_b32_e32 v92, v221, v92, vcc
	v_add_u32_e32 v203, 0x107, v204
	v_cndmask_b32_e64 v93, v221, v93, s[6:7]
	v_cmp_gt_u32_e32 vcc, s4, v102
	v_cmp_gt_u32_e64 s[6:7], s4, v203
	v_add_u32_e32 v102, 0x106, v204
	v_cndmask_b32_e32 v94, v221, v94, vcc
	v_add_u32_e32 v203, 0x105, v204
	v_cndmask_b32_e64 v95, v221, v95, s[6:7]
	v_cmp_gt_u32_e32 vcc, s4, v102
	v_cmp_gt_u32_e64 s[6:7], s4, v203
	v_add_u32_e32 v102, 0x100, v204
	v_cndmask_b32_e32 v96, v221, v96, vcc
	v_add_u32_e32 v203, 0xff, v204
	v_cndmask_b32_e64 v97, v221, v97, s[6:7]
	v_cmp_gt_u32_e32 vcc, s4, v102
	v_cmp_gt_u32_e64 s[6:7], s4, v203
	v_add_u32_e32 v102, 0xfe, v204
	v_cndmask_b32_e32 v66, v221, v66, vcc
	v_add_u32_e32 v203, 0xfd, v204
	v_cndmask_b32_e64 v67, v221, v67, s[6:7]
	v_cmp_gt_u32_e32 vcc, s4, v102
	v_cmp_gt_u32_e64 s[6:7], s4, v203
	v_add_u32_e32 v102, 0xf8, v204
	v_cndmask_b32_e32 v68, v221, v68, vcc
	v_add_u32_e32 v203, 0xf7, v204
	v_cndmask_b32_e64 v69, v221, v69, s[6:7]
	v_cmp_gt_u32_e32 vcc, s4, v102
	v_cmp_gt_u32_e64 s[6:7], s4, v203
	v_add_u32_e32 v102, 0xf6, v204
	v_cndmask_b32_e32 v70, v221, v70, vcc
	v_add_u32_e32 v203, 0xf5, v204
	v_cndmask_b32_e64 v71, v221, v71, s[6:7]
	v_cmp_gt_u32_e32 vcc, s4, v102
	v_cmp_gt_u32_e64 s[6:7], s4, v203
	v_add_u32_e32 v102, 0xf0, v204
	v_cndmask_b32_e32 v72, v221, v72, vcc
	v_add_u32_e32 v203, 0xef, v204
	v_cndmask_b32_e64 v73, v221, v73, s[6:7]
	v_cmp_gt_u32_e32 vcc, s4, v102
	v_cmp_gt_u32_e64 s[6:7], s4, v203
	v_add_u32_e32 v102, 0xee, v204
	v_cndmask_b32_e32 v74, v221, v74, vcc
	v_add_u32_e32 v203, 0xed, v204
	v_cndmask_b32_e64 v75, v221, v75, s[6:7]
	v_cmp_gt_u32_e32 vcc, s4, v102
	v_cmp_gt_u32_e64 s[6:7], s4, v203
	v_add_u32_e32 v102, 0xe8, v204
	v_cndmask_b32_e32 v76, v221, v76, vcc
	v_add_u32_e32 v203, 0xe7, v204
	v_cndmask_b32_e64 v77, v221, v77, s[6:7]
	v_cmp_gt_u32_e32 vcc, s4, v102
	v_cmp_gt_u32_e64 s[6:7], s4, v203
	v_add_u32_e32 v102, 0xe6, v204
	v_cndmask_b32_e32 v78, v221, v78, vcc
	v_add_u32_e32 v203, 0xe5, v204
	v_cndmask_b32_e64 v79, v221, v79, s[6:7]
	v_cmp_gt_u32_e32 vcc, s4, v102
	v_cmp_gt_u32_e64 s[6:7], s4, v203
	s_nop 1
	v_cndmask_b32_e32 v80, v221, v80, vcc
	v_cndmask_b32_e64 v81, v221, v81, s[6:7]
	v_max3_f32 v101, v82, v221, v83
	v_max3_f32 v101, v101, v84, v85
	v_max3_f32 v101, v101, v86, v87
	v_max3_f32 v101, v101, v88, v89
	v_max3_f32 v101, v101, v90, v91
	v_max3_f32 v101, v101, v92, v93
	v_max3_f32 v101, v101, v94, v95
	v_max3_f32 v101, v101, v96, v97
	v_max3_f32 v101, v101, v66, v67
	v_max3_f32 v101, v101, v68, v69
	v_max3_f32 v101, v101, v70, v71
	v_max3_f32 v101, v101, v72, v73
	v_max3_f32 v101, v101, v74, v75
	v_max3_f32 v101, v101, v76, v77
	v_max3_f32 v101, v101, v78, v79
	v_max3_f32 v101, v101, v80, v81
